# SSD Y stage: LDS fragment reads hand-scheduled ahead of their MFMAs; causal ks branches dropped (zero G fragments)
# speedup vs baseline: 1.0070x; 1.0070x over previous
; __device__ __forceinline__ u16 f2bf(float f) { return (u16)(cvt_pk(f, 0.f) & 0xffffu); }
; __device__ __forceinline__ void phaseA(const Params& p, const int wv, const int rep) {
;     ...
;   for (int i = blockIdx.x * NTHREADS + tid; i < 16384; i += gridDim.x * NTHREADS) {
;     int k = i & 1023, hh = i >> 10;
;     ((u16*)(ws + OFF_WDT))[i] = f2bf(p.in[8][(size_t)k * 7184 + 3584 + hh]);
;   }
.LBB0_110:
	s_nop 1
	v_readlane_b32 s0, v251, 1
	s_nop 3
	s_sub_u32 s0, s0, 1
	s_sub_u32 s0, s0, s1
	v_lshl_add_u32 v6, s0, 9, v40
	s_movk_i32 s0, 0x4000
	v_cmp_gt_i32_e32 vcc, s0, v6
	s_and_saveexec_b64 s[0:1], vcc
	s_cbranch_execz .LBB0_113
	s_add_u32 s2, s50, 0x1240e000
	v_readlane_b32 s8, v251, 1
	s_addc_u32 s3, s51, 0
	s_lshl_b32 s10, s8, 9
	s_mov_b64 s[8:9], 0
	v_mov_b32_e32 v3, 0
	s_movk_i32 s11, 0x3fff
	v_mov_b32_e32 v4, v6

; __device__ __forceinline__ void phaseA(const Params& p, const int wv, const int rep) {
;     ...
;   for (int i = blockIdx.x * NTHREADS + tid; i < 128 * 3072; i += gridDim.x * NTHREADS) {
;     int b = i / 3072, rem = i - b * 3072;
;     p.out[O_CONVS + (size_t)b * 4608 + rem] = p.in[5][(size_t)b * 4608 + 1536 + rem];
;   }
.LBB0_118:
	s_or_b64 exec, exec, s[0:1]
	v_readlane_b32 s0, v251, 0
	s_nop 3
	v_lshl_add_u32 v6, s0, 9, v40
	s_mov_b32 s0, 0x60000
	v_cmp_gt_i32_e32 vcc, s0, v6
	s_and_saveexec_b64 s[0:1], vcc
	v_readlane_b32 s56, v251, 6
	v_readlane_b32 s66, v251, 16
	v_readlane_b32 s67, v251, 17
	v_readlane_b32 s57, v251, 7
	v_readlane_b32 s58, v251, 8
	v_readlane_b32 s59, v251, 9
	v_readlane_b32 s60, v251, 10
	v_readlane_b32 s61, v251, 11
	v_readlane_b32 s62, v251, 12
	v_readlane_b32 s63, v251, 13
	v_readlane_b32 s64, v251, 14
	v_readlane_b32 s65, v251, 15
	v_readlane_b32 s68, v251, 18
	v_readlane_b32 s69, v251, 19
	v_readlane_b32 s70, v251, 20
	v_readlane_b32 s71, v251, 21
	s_cbranch_execz .LBB0_121
	v_readlane_b32 s8, v251, 1
	s_lshl_b32 s10, s8, 9
	s_mov_b64 s[8:9], 0
	s_mov_b32 s11, 0x2aaaaaab
	s_movk_i32 s12, 0xf400
	s_movk_i32 s13, 0x1000
	s_mov_b32 s14, 0x5ffff
	s_cmp_lg_u32 s10, 0x20000
	s_cbranch_scc1 .LBB0_120
	v_mov_b32_e32 v100, v6
	v_mul_hi_i32 v102, v100, s11
	v_lshrrev_b32_e32 v103, 31, v102
	v_ashrrev_i32_e32 v102, 9, v102
	v_add_u32_e32 v103, v102, v103
	v_mad_i32_i24 v102, v103, s12, v100
	v_mul_hi_i32_i24_e32 v105, 0x1200, v103
	v_mul_i32_i24_e32 v104, 0x1200, v103
	v_ashrrev_i32_e32 v103, 31, v102
	v_lshlrev_b64 v[104:105], 2, v[104:105]
	v_lshl_add_u64 v[106:107], s[66:67], 0, v[104:105]
	v_lshlrev_b64 v[102:103], 2, v[102:103]
	v_lshl_add_u64 v[106:107], v[106:107], 0, v[102:103]
	v_add_co_u32_e32 v106, vcc, s13, v106
	s_nop 1
	v_addc_co_u32_e32 v107, vcc, 0, v107, vcc
	global_load_dword v101, v[106:107], off offset:2048
	v_lshl_add_u64 v[104:105], s[48:49], 0, v[104:105]
	v_lshl_add_u64 v[102:103], v[104:105], 0, v[102:103]
	v_add_co_u32_e32 v102, vcc, 0x4ca4000, v102
	s_nop 1
	v_addc_co_u32_e32 v103, vcc, 0, v103, vcc
	v_add_u32_e32 v110, 0x20000, v6
	v_mul_hi_i32 v112, v110, s11
	v_lshrrev_b32_e32 v113, 31, v112
	v_ashrrev_i32_e32 v112, 9, v112
	v_add_u32_e32 v113, v112, v113
	v_mad_i32_i24 v112, v113, s12, v110
	v_mul_hi_i32_i24_e32 v115, 0x1200, v113
	v_mul_i32_i24_e32 v114, 0x1200, v113
	v_ashrrev_i32_e32 v113, 31, v112
	v_lshlrev_b64 v[114:115], 2, v[114:115]
	v_lshl_add_u64 v[116:117], s[66:67], 0, v[114:115]
	v_lshlrev_b64 v[112:113], 2, v[112:113]
	v_lshl_add_u64 v[116:117], v[116:117], 0, v[112:113]
	v_add_co_u32_e32 v116, vcc, s13, v116
	s_nop 1
	v_addc_co_u32_e32 v117, vcc, 0, v117, vcc
	global_load_dword v111, v[116:117], off offset:2048
	v_lshl_add_u64 v[114:115], s[48:49], 0, v[114:115]
	v_lshl_add_u64 v[112:113], v[114:115], 0, v[112:113]
	v_add_co_u32_e32 v112, vcc, 0x4ca4000, v112
	s_nop 1
	v_addc_co_u32_e32 v113, vcc, 0, v113, vcc
	v_add_u32_e32 v120, 0x40000, v6
	v_mul_hi_i32 v122, v120, s11
	v_lshrrev_b32_e32 v123, 31, v122
	v_ashrrev_i32_e32 v122, 9, v122
	v_add_u32_e32 v123, v122, v123
	v_mad_i32_i24 v122, v123, s12, v120
	v_mul_hi_i32_i24_e32 v125, 0x1200, v123
	v_mul_i32_i24_e32 v124, 0x1200, v123
	v_ashrrev_i32_e32 v123, 31, v122
	v_lshlrev_b64 v[124:125], 2, v[124:125]
	v_lshl_add_u64 v[126:127], s[66:67], 0, v[124:125]
	v_lshlrev_b64 v[122:123], 2, v[122:123]
	v_lshl_add_u64 v[126:127], v[126:127], 0, v[122:123]
	v_add_co_u32_e32 v126, vcc, s13, v126
	s_nop 1
	v_addc_co_u32_e32 v127, vcc, 0, v127, vcc
	global_load_dword v121, v[126:127], off offset:2048
	v_lshl_add_u64 v[124:125], s[48:49], 0, v[124:125]
	v_lshl_add_u64 v[122:123], v[124:125], 0, v[122:123]
	v_add_co_u32_e32 v122, vcc, 0x4ca4000, v122
	s_nop 1
	v_addc_co_u32_e32 v123, vcc, 0, v123, vcc
	s_waitcnt vmcnt(2)
	global_store_dword v[102:103], v101, off
	s_waitcnt vmcnt(1)
	global_store_dword v[112:113], v111, off
	s_waitcnt vmcnt(0)
	global_store_dword v[122:123], v121, off
	s_branch .LBB0_121

; #define MFMA16(a, b, c) __builtin_amdgcn_mfma_f32_16x16x32_bf16((a), (b), (c), 0, 0, 0)
; __device__ __forceinline__ void ssd_prompt_item(const Params& p, int item, const int wv) {
;     ...
;       const int i = wid * 16 + fr, tok = t0 + i;
;       const float ea = __expf(acum_l[i]);
;       float ss = 0.f;
;       u32x2 ypk[4];
;       bf16x8 gf[4];
; #pragma unroll
;       for (int ks = 0; ks < 4; ++ks) gf[ks] = *(const bf16x8*)(G_l + (wid * 16 + fr) * 136 + ks * 32 + fq * 8);
; #pragma unroll
;       for (int pb = 0; pb < 4; ++pb) {
;         f32x4 y = {0.f, 0.f, 0.f, 0.f};
; #pragma unroll
;         for (int ks = 0; ks < 4; ++ks) { bf16x8 hf = *(const bf16x8*)(h_l + (pb * 16 + fr) * 136 + ks * 32 + fq * 8); y = MFMA16(hf, cf[ks], y); }
;         y = y * ea;
; #pragma unroll
;         for (int ks = 0; ks < 4; ++ks) {
;           if (ks <= (wid >> 1)) {
;             bf16x8 xf = *(const bf16x8*)(xT_l + (pb * 16 + fr) * 136 + ks * 32 + fq * 8);
;             y = MFMA16(xf, gf[ks], y);
;           }
;         }
.LBB0_607:
	v_cvt_pk_bf16_f32 v96, v96, v97
	v_cvt_pk_bf16_f32 v97, v98, v99
	ds_write_b64 v124, v[96:97] offset:35040
	s_waitcnt lgkmcnt(0)
	s_barrier
	ds_read_b128 v[112:115], v142 offset:34816
	ds_read_b128 v[108:111], v142 offset:34880
	ds_read_b128 v[104:107], v142 offset:34944
	ds_read_b128 v[96:99], v142 offset:35008
	ds_read_b32 v124, v197
	ds_read_b128 v[32:35], v224
	ds_read_b128 v[36:39], v224 offset:64
	ds_read_b128 v[150:153], v224 offset:128
	ds_read_b128 v[154:157], v224 offset:192
	ds_read_b128 v[162:165], v225
	ds_read_b128 v[170:173], v225 offset:64
	s_waitcnt lgkmcnt(6)
	v_mul_f32_e32 v124, 0x3fb8aa3b, v124
	v_exp_f32_e32 v124, v124
	ds_read_u16 v128, v226
	ds_read_u16 v129, v226 offset:272
	ds_read_u16 v126, v226 offset:544
	ds_read_u16 v127, v226 offset:816
	v_mov_b32_e32 v125, v124
	s_waitcnt lgkmcnt(9)
	v_mfma_f32_16x16x32_bf16 v[100:103], v[32:35], v[88:91], 0
	s_waitcnt lgkmcnt(8)
	v_mfma_f32_16x16x32_bf16 v[100:103], v[36:39], v[84:87], v[100:103]
	ds_read_b128 v[32:35], v225 offset:128
	s_waitcnt lgkmcnt(8)
	v_mfma_f32_16x16x32_bf16 v[100:103], v[150:153], v[80:83], v[100:103]
	ds_read_b128 v[36:39], v225 offset:192
	s_waitcnt lgkmcnt(8)
	v_mfma_f32_16x16x32_bf16 v[100:103], v[154:157], v[92:95], v[100:103]
	ds_read_b128 v[150:153], v224 offset:4352
	ds_read_b128 v[154:157], v224 offset:4416
	ds_read_u16 v140, v226 offset:4352
	ds_read_u16 v141, v226 offset:4624
	ds_read_u16 v130, v226 offset:4896
	ds_read_u16 v131, v226 offset:5168
	s_nop 1
	v_pk_mul_f32 v[100:101], v[100:101], v[124:125]
	v_pk_mul_f32 v[102:103], v[102:103], v[124:125]
	s_nop 1
	s_waitcnt lgkmcnt(13)
	v_mfma_f32_16x16x32_bf16 v[100:103], v[162:165], v[112:115], v[100:103]
	s_waitcnt lgkmcnt(12)
	v_mfma_f32_16x16x32_bf16 v[100:103], v[170:173], v[108:111], v[100:103]
	ds_read_b128 v[162:165], v224 offset:4480
	s_waitcnt lgkmcnt(8)
	v_mfma_f32_16x16x32_bf16 v[100:103], v[32:35], v[104:107], v[100:103]
	ds_read_b128 v[170:173], v224 offset:4544
	s_waitcnt lgkmcnt(8)
	v_mfma_f32_16x16x32_bf16 v[100:103], v[36:39], v[96:99], v[100:103]
	ds_read_b128 v[32:35], v225 offset:4352
	ds_read_b128 v[36:39], v225 offset:4416
	s_waitcnt lgkmcnt(9)
	v_mfma_f32_16x16x32_bf16 v[116:119], v[150:153], v[88:91], 0
	s_waitcnt lgkmcnt(8)
	v_mfma_f32_16x16x32_bf16 v[116:119], v[154:157], v[84:87], v[116:119]
	ds_read_b128 v[150:153], v225 offset:4480
	s_waitcnt lgkmcnt(4)
	v_mfma_f32_16x16x32_bf16 v[116:119], v[162:165], v[80:83], v[116:119]
	ds_read_b128 v[154:157], v225 offset:4544
	s_waitcnt lgkmcnt(4)
	v_mfma_f32_16x16x32_bf16 v[116:119], v[170:173], v[92:95], v[116:119]
	ds_read_b128 v[162:165], v224 offset:8704
	ds_read_b128 v[170:173], v224 offset:8768
	ds_read_u16 v191, v226 offset:8704
	ds_read_u16 v228, v226 offset:8976
	ds_read_u16 v142, v226 offset:9248
	ds_read_u16 v190, v226 offset:9520
	s_nop 1
	v_pk_mul_f32 v[116:117], v[116:117], v[124:125]
	v_pk_mul_f32 v[118:119], v[118:119], v[124:125]
	s_nop 1
	s_waitcnt lgkmcnt(9)
	v_mfma_f32_16x16x32_bf16 v[116:119], v[32:35], v[112:115], v[116:119]
	s_waitcnt lgkmcnt(8)
	v_mfma_f32_16x16x32_bf16 v[116:119], v[36:39], v[108:111], v[116:119]
	ds_read_b128 v[32:35], v224 offset:8832
	s_waitcnt lgkmcnt(8)
	v_mfma_f32_16x16x32_bf16 v[116:119], v[150:153], v[104:107], v[116:119]
	ds_read_b128 v[36:39], v224 offset:8896
	s_waitcnt lgkmcnt(8)
	v_mfma_f32_16x16x32_bf16 v[116:119], v[154:157], v[96:99], v[116:119]
	ds_read_b128 v[150:153], v225 offset:8704
	ds_read_b128 v[154:157], v225 offset:8768
	s_waitcnt lgkmcnt(9)
	v_mfma_f32_16x16x32_bf16 v[120:123], v[162:165], v[88:91], 0
	s_waitcnt lgkmcnt(8)
	v_mfma_f32_16x16x32_bf16 v[120:123], v[170:173], v[84:87], v[120:123]
	ds_read_b128 v[162:165], v225 offset:8832
	s_waitcnt lgkmcnt(4)
	v_mfma_f32_16x16x32_bf16 v[120:123], v[32:35], v[80:83], v[120:123]
	ds_read_b128 v[170:173], v225 offset:8896
	s_waitcnt lgkmcnt(4)
	v_mfma_f32_16x16x32_bf16 v[120:123], v[36:39], v[92:95], v[120:123]
	ds_read_b128 v[32:35], v224 offset:13056
	ds_read_b128 v[36:39], v224 offset:13120
	s_nop 3
	s_nop 1
	v_pk_mul_f32 v[120:121], v[120:121], v[124:125]
	v_pk_mul_f32 v[122:123], v[122:123], v[124:125]
	s_nop 1
	s_waitcnt lgkmcnt(5)
	v_mfma_f32_16x16x32_bf16 v[120:123], v[150:153], v[112:115], v[120:123]
	s_waitcnt lgkmcnt(4)
	v_mfma_f32_16x16x32_bf16 v[120:123], v[154:157], v[108:111], v[120:123]
	ds_read_b128 v[150:153], v224 offset:13184
	s_waitcnt lgkmcnt(4)
	v_mfma_f32_16x16x32_bf16 v[120:123], v[162:165], v[104:107], v[120:123]
	ds_read_b128 v[154:157], v224 offset:13248
	s_waitcnt lgkmcnt(4)
	v_mfma_f32_16x16x32_bf16 v[120:123], v[170:173], v[96:99], v[120:123]
	ds_read_b128 v[162:165], v225 offset:13056
	ds_read_b128 v[170:173], v225 offset:13120
	s_waitcnt lgkmcnt(5)
	v_mfma_f32_16x16x32_bf16 v[236:239], v[32:35], v[88:91], 0
	s_waitcnt lgkmcnt(4)
	v_mfma_f32_16x16x32_bf16 v[236:239], v[36:39], v[84:87], v[236:239]
	ds_read_b128 v[32:35], v225 offset:13184
	s_waitcnt lgkmcnt(4)
	v_mfma_f32_16x16x32_bf16 v[236:239], v[150:153], v[80:83], v[236:239]
	ds_read_b128 v[36:39], v225 offset:13248
	s_waitcnt lgkmcnt(4)
	v_mfma_f32_16x16x32_bf16 v[236:239], v[154:157], v[92:95], v[236:239]
	s_nop 7
	s_nop 1
	v_pk_mul_f32 v[236:237], v[236:237], v[124:125]
	v_pk_mul_f32 v[238:239], v[238:239], v[124:125]
	s_nop 1
	s_waitcnt lgkmcnt(3)
	v_mfma_f32_16x16x32_bf16 v[236:239], v[162:165], v[112:115], v[236:239]
	s_waitcnt lgkmcnt(2)
	v_mfma_f32_16x16x32_bf16 v[236:239], v[170:173], v[108:111], v[236:239]
	s_waitcnt lgkmcnt(1)
	v_mfma_f32_16x16x32_bf16 v[236:239], v[32:35], v[104:107], v[236:239]
	s_waitcnt lgkmcnt(0)
	v_mfma_f32_16x16x32_bf16 v[80:83], v[36:39], v[96:99], v[236:239]
; __device__ __forceinline__ u32x2 pack4(f32x4 v) { u32x2 r; r.x = cvt_pk(v[0], v[1]); r.y = cvt_pk(v[2], v[3]); return r; }
; __device__ __forceinline__ float bf2f(u16 h) { return __uint_as_float(((unsigned)h) << 16); }
; __device__ __forceinline__ f32x4 unpack4(u32x2 w) { return (f32x4){bflo(w.x), bfhi(w.x), bflo(w.y), bfhi(w.y)}; }
; __device__ __forceinline__ int lane_fresh() { int l; asm volatile("v_mbcnt_lo_u32_b32 %0, -1, 0\n\tv_mbcnt_hi_u32_b32 %0, -1, %0" : "=v"(l)); return l; }
; __device__ __forceinline__ float shfl_xor_f(float v, int mask) { const int l = lane_fresh(); return __int_as_float(__builtin_amdgcn_ds_bpermute((l ^ mask) << 2, __float_as_int(v))); }
; #define LAS __attribute__((address_space(3)))
; __device__ __forceinline__ unsigned xb_xcc_id() { return (unsigned)__builtin_amdgcn_s_getreg((3 << 11) | 20) & 0xFu; }
; __device__ __forceinline__ void xcd_barrier(unsigned* bar, const int wv) {
;   asm volatile("s_waitcnt vmcnt(0)" ::: "memory");
;   __syncthreads();
;   if (wv == 0) {
;     if (lane_fresh() == 0) {
;       volatile LAS unsigned* st = (volatile LAS unsigned*)&xb_words;
;       const unsigned x = xb_xcc_id();
;       __builtin_amdgcn_s_waitcnt(0);
;       unsigned nloc = st[0], nx = st[1];
;       if (nloc == 0u) { xcd_barrier_complete(bar, x, nloc, nx); st[0] = nloc; st[1] = nx; }
; __device__ __forceinline__ void ssd_prompt_item(const Params& p, int item, const int wv) {
;     ...
;         const int pc = pb * 16 + fq * 4;
;         f32x4 zs = unpack4(zsr[pb]);
; #pragma unroll
;         for (int e = 0; e < 4; ++e) { float xv = bf2f(xT_l[(pc + e) * 136 + i]); y[e] = (y[e] + xv * Dh) * zs[e]; ss += y[e] * y[e]; }
;         ypk[pb] = pack4(y);
;       }
;       store_pair16(Y + (size_t)tok * 1024 + h * 64, ypk[0], ypk[1], fq);
;       store_pair16(Y + (size_t)tok * 1024 + h * 64 + 32, ypk[2], ypk[3], fq);
;       ss += shfl_xor_f(ss, 16); ss += shfl_xor_f(ss, 32);
;       if (fq == 0) { YPS[(size_t)tok * 32 + g * 16 + (h & 7) * 2] = ss; YPS[(size_t)tok * 32 + g * 16 + (h & 7) * 2 + 1] = 0.f; }
.LBB0_623:
	v_lshlrev_b32_e32 v87, 16, v129
	v_lshlrev_b32_e32 v86, 16, v128
	s_waitcnt vmcnt(3)
	v_lshlrev_b32_e32 v84, 16, v138
	v_and_b32_e32 v85, 0xffff0000, v138
	v_pk_fma_f32 v[86:87], v[144:145], v[86:87], v[100:101]
	v_lshlrev_b32_e32 v89, 16, v127
	v_lshlrev_b32_e32 v88, 16, v126
	v_pk_mul_f32 v[86:87], v[86:87], v[84:85]
	v_lshlrev_b32_e32 v84, 16, v139
	v_and_b32_e32 v85, 0xffff0000, v139
	v_pk_fma_f32 v[88:89], v[144:145], v[88:89], v[102:103]
	v_lshlrev_b32_e32 v91, 16, v131
	v_pk_mul_f32 v[94:95], v[88:89], v[84:85]
	v_lshlrev_b32_e32 v89, 16, v141
	v_lshlrev_b32_e32 v88, 16, v140
	s_waitcnt vmcnt(2)
	v_lshlrev_b32_e32 v84, 16, v136
	v_and_b32_e32 v85, 0xffff0000, v136
	v_pk_fma_f32 v[88:89], v[144:145], v[88:89], v[116:117]
	v_lshlrev_b32_e32 v90, 16, v130
	v_pk_mul_f32 v[88:89], v[88:89], v[84:85]
	v_lshlrev_b32_e32 v84, 16, v137
	v_and_b32_e32 v85, 0xffff0000, v137
	v_pk_fma_f32 v[90:91], v[144:145], v[90:91], v[118:119]
	v_pk_mul_f32 v[92:93], v[86:87], v[86:87]
	v_pk_mul_f32 v[100:101], v[90:91], v[84:85]
	v_lshlrev_b32_e32 v91, 16, v228
	v_lshlrev_b32_e32 v90, 16, v191
	s_waitcnt vmcnt(1)
	v_lshlrev_b32_e32 v84, 16, v134
	v_and_b32_e32 v85, 0xffff0000, v134
	v_pk_fma_f32 v[90:91], v[144:145], v[90:91], v[120:121]
	v_lshlrev_b32_e32 v107, 16, v190
	v_lshlrev_b32_e32 v106, 16, v142
	v_pk_mul_f32 v[96:97], v[94:95], v[94:95]
	v_pk_mul_f32 v[84:85], v[90:91], v[84:85]
	v_lshlrev_b32_e32 v90, 16, v135
	v_and_b32_e32 v91, 0xffff0000, v135
	v_pk_fma_f32 v[106:107], v[144:145], v[106:107], v[122:123]
	v_add_f32_e32 v92, v92, v93
	v_pk_mul_f32 v[90:91], v[106:107], v[90:91]
	v_add_f32_e32 v92, v92, v96
	v_pk_mul_f32 v[98:99], v[88:89], v[88:89]
	v_pk_mul_f32 v[104:105], v[84:85], v[84:85]
	v_pk_mul_f32 v[106:107], v[90:91], v[90:91]
	v_cvt_pk_bf16_f32 v84, v84, v85
	v_cvt_pk_bf16_f32 v85, v90, v91
	v_cvt_pk_bf16_f32 v90, v88, v89
	v_cvt_pk_bf16_f32 v89, v94, v95
	ds_read_u16 v94, v226 offset:13056
	ds_read_u16 v95, v226 offset:13328
	v_add_f32_e32 v92, v92, v97
	v_add_f32_e32 v92, v92, v98
	v_pk_mul_f32 v[102:103], v[100:101], v[100:101]
	v_cvt_pk_bf16_f32 v91, v100, v101
	ds_read_u16 v100, v226 offset:13600
	ds_read_u16 v101, v226 offset:13872
	v_add_f32_e32 v92, v92, v99
	v_add_f32_e32 v92, v92, v102
	v_add_f32_e32 v92, v92, v103
	s_waitcnt lgkmcnt(2)
	v_lshlrev_b32_e32 v95, 16, v95
	v_lshlrev_b32_e32 v94, 16, v94
	v_add_f32_e32 v92, v92, v104
	v_cvt_pk_bf16_f32 v88, v86, v87
	s_waitcnt vmcnt(0)
	v_lshlrev_b32_e32 v86, 16, v132
	v_and_b32_e32 v87, 0xffff0000, v132
	v_pk_fma_f32 v[80:81], v[144:145], v[94:95], v[80:81]
	v_add_f32_e32 v92, v92, v105
	v_pk_mul_f32 v[80:81], v[80:81], v[86:87]
	s_waitcnt lgkmcnt(0)
	v_lshlrev_b32_e32 v101, 16, v101
	v_lshlrev_b32_e32 v100, 16, v100
	v_add_f32_e32 v92, v92, v106
	v_pk_mul_f32 v[86:87], v[80:81], v[80:81]
	v_lshlrev_b32_e32 v94, 16, v133
	v_and_b32_e32 v95, 0xffff0000, v133
	v_pk_fma_f32 v[82:83], v[144:145], v[100:101], v[82:83]
	v_add_f32_e32 v92, v92, v107
	v_pk_mul_f32 v[82:83], v[82:83], v[94:95]
	v_add_f32_e32 v86, v92, v86
	v_pk_mul_f32 v[94:95], v[82:83], v[82:83]
	v_add_f32_e32 v86, v86, v87
	v_add_f32_e32 v86, v86, v94
	v_add_f32_e32 v92, v86, v95
	v_cvt_pk_bf16_f32 v86, v80, v81
	v_cvt_pk_bf16_f32 v87, v82, v83
	v_permlane16_swap_b32_e32 v88, v90
	v_permlane16_swap_b32_e32 v89, v91
	v_permlane16_swap_b32_e32 v84, v86
	v_permlane16_swap_b32_e32 v85, v87
	global_store_dwordx4 v[188:189], v[88:91], off offset:-64
	global_store_dwordx4 v[188:189], v[84:87], off
	v_mbcnt_lo_u32_b32 v80, -1, 0
	v_mbcnt_hi_u32_b32 v80, -1, v80
	v_mbcnt_lo_u32_b32 v81, -1, 0
	v_mbcnt_hi_u32_b32 v81, -1, v81
	s_nop 0
	v_lshlrev_b32_e32 v80, 2, v80
	v_xor_b32_e32 v80, 64, v80
	ds_bpermute_b32 v80, v80, v92
	v_lshlrev_b32_e32 v81, 2, v81
	v_xor_b32_e32 v81, 0x80, v81
	s_waitcnt lgkmcnt(0)
	v_add_f32_e32 v80, v92, v80
	ds_bpermute_b32 v81, v81, v80
	s_and_saveexec_b64 s[84:85], s[4:5]
	s_cbranch_execz .LBB0_569
	s_waitcnt lgkmcnt(0)
	v_add_f32_e32 v142, v80, v81
	v_lshl_add_u64 v[80:81], s[50:51], 0, v[184:185]
	v_add_co_u32_e32 v80, vcc, 0x2f22000, v80
	s_nop 1
	v_addc_co_u32_e32 v81, vcc, 0, v81, vcc
	global_store_dwordx2 v[80:81], v[142:143], off
	s_branch .LBB0_569
.LBB0_633:
	s_waitcnt vmcnt(0)
	v_readlane_b32 s0, v251, 58
	v_readlane_b32 s1, v251, 59
	s_and_b64 vcc, exec, s[0:1]
	s_mov_b32 s33, 1
	s_waitcnt lgkmcnt(0)
	s_barrier
	s_cbranch_vccnz .LBB0_687
	v_mbcnt_lo_u32_b32 v0, -1, 0
	v_mbcnt_hi_u32_b32 v0, -1, v0
	s_nop 0
	v_cmp_eq_u32_e32 vcc, 0, v0
	s_and_saveexec_b64 s[0:1], vcc
	s_cbranch_execz .LBB0_686
	v_mov_b32_e32 v0, 0
	s_getreg_b32 s2, hwreg(HW_REG_XCC_ID, 0, 4)
	s_waitcnt vmcnt(0) expcnt(0) lgkmcnt(0)
	ds_read_b32 v2, v0
	ds_read_b32 v1, v0 offset:4
	s_and_b32 s44, s2, 15
	s_waitcnt lgkmcnt(1)
	v_cmp_ne_u32_e32 vcc, 0, v2
	s_cbranch_vccnz .LBB0_650
	s_add_u32 s2, s50, 0x12416200
	s_addc_u32 s3, s51, 0
	s_add_u32 s4, s50, 0x12416400
	s_addc_u32 s5, s51, 0
	s_add_u32 s6, s50, 0x12416500
	s_addc_u32 s7, s51, 0
	s_add_u32 s8, s50, 0x12416600
	s_addc_u32 s9, s51, 0
	s_add_u32 s10, s50, 0x12416700
	s_addc_u32 s11, s51, 0
	s_add_u32 s12, s50, 0x12416800
	s_addc_u32 s13, s51, 0
	s_add_u32 s14, s50, 0x12416900
	s_addc_u32 s15, s51, 0
	s_add_u32 s16, s50, 0x12416a00
	s_addc_u32 s17, s51, 0
	s_add_u32 s18, s50, 0x12416b00
	s_addc_u32 s19, s51, 0
	s_add_u32 s20, s50, 0x12416c00
	s_addc_u32 s21, s51, 0
	s_add_u32 s22, s50, 0x12416d00
	s_addc_u32 s23, s51, 0
	s_add_u32 s24, s50, 0x12416e00
	s_addc_u32 s25, s51, 0
	s_add_u32 s26, s50, 0x12416f00
	s_addc_u32 s27, s51, 0
	s_add_u32 s28, s50, 0x12417000
	s_addc_u32 s29, s51, 0
	s_add_u32 s30, s50, 0x12417100
	s_addc_u32 s31, s51, 0
	s_add_u32 s34, s50, 0x12417200
	s_addc_u32 s35, s51, 0
	s_add_u32 s36, s50, 0x12417300
	s_addc_u32 s37, s51, 0
	s_mov_b32 s45, 1
	s_branch .LBB0_638
